# attention steady loops: 5 redundant VALU per step removed (NaN-canonicalising max pairs, +0 add)
# speedup vs baseline: 1.0069x; 1.0039x over previous
.LBB0_417:
	s_waitcnt lgkmcnt(7)
	v_mfma_f32_32x32x16_bf16 v[130:145], v[206:209], v[174:177], v[66:81]
	v_add_f32_e32 v114, v98, v99
	v_add_f32_e32 v114, v100, v114
	v_add_f32_e32 v114, v101, v114
	s_lshl_b32 s10, s10, 1
	v_add_f32_e32 v114, v102, v114
	v_add_u32_e32 v239, s10, v243
	v_add_f32_e32 v114, v103, v114
	v_cvt_pk_bf16_f32 v158, v98, v99
	v_cvt_pk_bf16_f32 v159, v100, v101
	s_nop 0
	v_add_f32_e32 v98, v104, v114
	s_waitcnt lgkmcnt(6)
	v_mfma_f32_32x32x16_bf16 v[114:129], v[202:205], v[174:177], v[66:81]
	v_add_f32_e32 v98, v105, v98
	v_add_f32_e32 v98, v106, v98
	v_add_f32_e32 v98, v107, v98
	v_cvt_pk_bf16_f32 v160, v102, v103
	v_cvt_pk_bf16_f32 v161, v104, v105
	s_waitcnt lgkmcnt(5)
	v_mfma_f32_32x32x16_bf16 v[130:145], v[198:201], v[170:173], v[130:145]
	v_add_f32_e32 v98, v108, v98
	v_add_f32_e32 v98, v109, v98
	v_add_f32_e32 v98, v110, v98
	v_add_f32_e32 v98, v111, v98
	v_cvt_pk_bf16_f32 v154, v106, v107
	v_cvt_pk_bf16_f32 v155, v108, v109
	s_waitcnt lgkmcnt(4)
	v_mfma_f32_32x32x16_bf16 v[114:129], v[194:197], v[170:173], v[114:129]
	v_add_f32_e32 v98, v112, v98
	v_add_f32_e32 v98, v113, v98
	v_add_f32_e32 v98, v82, v98
	v_add_f32_e32 v102, v83, v98
	v_cvt_pk_bf16_f32 v156, v110, v111
	v_cvt_pk_bf16_f32 v157, v112, v113
	ds_read_b64_tr_b16 v[98:99], v239 offset:24576
	ds_read_b64_tr_b16 v[100:101], v239 offset:25088
	s_waitcnt lgkmcnt(5)
	v_mfma_f32_32x32x16_bf16 v[130:145], v[190:193], v[166:169], v[130:145]
	v_add_f32_e32 v102, v84, v102
	v_add_f32_e32 v102, v85, v102
	v_add_f32_e32 v102, v86, v102
	v_add_f32_e32 v102, v87, v102
	v_cvt_pk_bf16_f32 v150, v82, v83
	v_cvt_pk_bf16_f32 v151, v84, v85
	ds_read_b64_tr_b16 v[82:83], v239 offset:28672
	ds_read_b64_tr_b16 v[84:85], v239 offset:29184
	s_waitcnt lgkmcnt(6)
	v_mfma_f32_32x32x16_bf16 v[114:129], v[186:189], v[166:169], v[114:129]
	v_add_f32_e32 v102, v88, v102
	v_add_f32_e32 v102, v89, v102
	v_add_f32_e32 v102, v90, v102
	v_add_f32_e32 v102, v91, v102
	v_cvt_pk_bf16_f32 v152, v86, v87
	v_cvt_pk_bf16_f32 v153, v88, v89
	ds_read_b64_tr_b16 v[86:87], v239 offset:25600
	ds_read_b64_tr_b16 v[88:89], v239 offset:26112
	s_waitcnt lgkmcnt(7)
	v_mfma_f32_32x32x16_bf16 v[130:145], v[182:185], v[162:165], v[130:145]
	v_add_f32_e32 v102, v92, v102
	v_add_f32_e32 v102, v93, v102
	v_add_f32_e32 v102, v94, v102
	v_add_f32_e32 v102, v95, v102
	v_cvt_pk_bf16_f32 v146, v90, v91
	v_cvt_pk_bf16_f32 v147, v92, v93
	ds_read_b64_tr_b16 v[90:91], v239 offset:29696
	ds_read_b64_tr_b16 v[92:93], v239 offset:30208
	s_waitcnt lgkmcnt(8)
	v_mfma_f32_32x32x16_bf16 v[114:129], v[178:181], v[162:165], v[114:129]
	v_add_f32_e32 v102, v96, v102
	v_add_f32_e32 v102, v97, v102
	v_cvt_pk_bf16_f32 v148, v94, v95
	v_cvt_pk_bf16_f32 v149, v96, v97
	v_lshl_add_u64 v[208:209], v[234:235], 0, s[20:21]
	v_lshl_add_u64 v[94:95], v[208:209], 0, s[46:47]
	s_add_i32 s10, s68, s41
	v_lshl_add_u64 v[206:207], v[236:237], 0, s[20:21]
	s_mov_b32 s11, m0
	s_mov_b32 m0, s10
	s_nop 0
	global_load_lds_dwordx4 v[94:95], off
	s_mov_b32 m0, s11
	v_lshl_add_u64 v[94:95], v[206:207], 0, s[48:49]
	s_lshl_b32 s10, s5, 1
	s_add_i32 s10, s10, s57
	s_mov_b32 s11, m0
	s_mov_b32 m0, s10
	s_nop 0
	global_load_lds_dwordx4 v[94:95], off
	s_mov_b32 m0, s11
	v_lshl_add_u64 v[94:95], v[206:207], 0, s[50:51]
	s_addk_i32 s10, 0x2000
	s_mov_b32 s11, m0
	s_mov_b32 m0, s10
	s_nop 0
	global_load_lds_dwordx4 v[94:95], off
	s_mov_b32 m0, s11
	v_max_f32_e32 v94, v130, v131
	v_max3_f32 v95, v132, v133, v115
	v_max3_f32 v94, v94, v114, v116
	v_max3_f32 v94, v94, v117, v134
	v_max3_f32 v95, v95, v136, v137
	v_max3_f32 v94, v94, v135, v118
	v_max3_f32 v95, v95, v120, v121
	v_max3_f32 v94, v94, v119, v138
	v_max3_f32 v95, v95, v140, v141
	v_max3_f32 v94, v94, v139, v122
	v_max3_f32 v95, v95, v124, v125
	v_max3_f32 v94, v94, v123, v142
	v_max3_f32 v95, v95, v144, v145
	v_max3_f32 v94, v94, v143, v126
	v_max3_f32 v95, v95, v128, v129
	v_max3_f32 v94, v94, v127, v95
	v_mov_b32_e32 v95, v94
	s_nop 1
	v_permlane32_swap_b32_e32 v94, v95
	v_max_f32_e32 v94, v94, v95
	v_cmp_lt_f32_e32 vcc, s84, v94
	s_cmp_lg_u64 vcc, 0
	v_add_f32_e32 v238, v238, v102
	s_cselect_b64 s[58:59], -1, 0
	s_cbranch_vccnz .LBB0_425

.LBB0_420:
	s_add_i32 s10, s5, 0x2000
	s_cmpk_lg_i32 s5, 0x4000
	s_cselect_b32 s88, s10, 0
	v_mfma_f32_32x32x16_bf16 v[98:113], v[82:85], v[174:177], v[66:81]
	v_add_f32_e32 v86, v130, v131
	v_add_f32_e32 v86, v132, v86
	v_add_f32_e32 v86, v133, v86
	s_lshl_b32 s10, s68, 1
	v_add_f32_e32 v86, v134, v86
	v_add_u32_e32 v239, s10, v243
	v_add_f32_e32 v82, v135, v86
	v_cvt_pk_bf16_f32 v158, v130, v131
	v_cvt_pk_bf16_f32 v159, v132, v133
	s_nop 0
	v_add_f32_e32 v82, v136, v82
	v_add_f32_e32 v82, v137, v82
	v_add_f32_e32 v82, v138, v82
	v_add_f32_e32 v130, v139, v82
	v_mfma_f32_32x32x16_bf16 v[82:97], v[198:201], v[174:177], v[66:81]
	v_cvt_pk_bf16_f32 v160, v134, v135
	v_cvt_pk_bf16_f32 v161, v136, v137
	v_mfma_f32_32x32x16_bf16 v[98:113], v[202:205], v[170:173], v[98:113]
	v_add_f32_e32 v130, v140, v130
	v_add_f32_e32 v130, v141, v130
	v_add_f32_e32 v130, v142, v130
	v_add_f32_e32 v130, v143, v130
	v_cvt_pk_bf16_f32 v154, v138, v139
	v_cvt_pk_bf16_f32 v155, v140, v141
	v_mfma_f32_32x32x16_bf16 v[82:97], v[194:197], v[170:173], v[82:97]
	v_add_f32_e32 v130, v144, v130
	v_add_f32_e32 v130, v145, v130
	v_add_f32_e32 v130, v114, v130
	v_add_f32_e32 v134, v115, v130
	v_cvt_pk_bf16_f32 v156, v142, v143
	v_cvt_pk_bf16_f32 v157, v144, v145
	ds_read_b64_tr_b16 v[130:131], v239 offset:24576
	ds_read_b64_tr_b16 v[132:133], v239 offset:25088
	v_mfma_f32_32x32x16_bf16 v[98:113], v[190:193], v[166:169], v[98:113]
	v_add_f32_e32 v134, v116, v134
	v_add_f32_e32 v134, v117, v134
	v_add_f32_e32 v134, v118, v134
	v_add_f32_e32 v134, v119, v134
	v_cvt_pk_bf16_f32 v150, v114, v115
	v_cvt_pk_bf16_f32 v151, v116, v117
	ds_read_b64_tr_b16 v[114:115], v239 offset:28672
	ds_read_b64_tr_b16 v[116:117], v239 offset:29184
	v_mfma_f32_32x32x16_bf16 v[82:97], v[186:189], v[166:169], v[82:97]
	v_add_f32_e32 v134, v120, v134
	v_add_f32_e32 v134, v121, v134
	v_add_f32_e32 v134, v122, v134
	v_add_f32_e32 v134, v123, v134
	v_cvt_pk_bf16_f32 v152, v118, v119
	v_cvt_pk_bf16_f32 v153, v120, v121
	ds_read_b64_tr_b16 v[118:119], v239 offset:25600
	ds_read_b64_tr_b16 v[120:121], v239 offset:26112
	v_mfma_f32_32x32x16_bf16 v[98:113], v[182:185], v[162:165], v[98:113]
	v_add_f32_e32 v134, v124, v134
	v_add_f32_e32 v134, v125, v134
	v_add_f32_e32 v134, v126, v134
	v_add_f32_e32 v134, v127, v134
	v_cvt_pk_bf16_f32 v146, v122, v123
	v_cvt_pk_bf16_f32 v147, v124, v125
	ds_read_b64_tr_b16 v[122:123], v239 offset:29696
	ds_read_b64_tr_b16 v[124:125], v239 offset:30208
	v_mfma_f32_32x32x16_bf16 v[82:97], v[178:181], v[162:165], v[82:97]
	v_add_f32_e32 v134, v128, v134
	v_add_f32_e32 v134, v129, v134
	v_cvt_pk_bf16_f32 v148, v126, v127
	v_cvt_pk_bf16_f32 v149, v128, v129
	v_lshl_add_u64 v[126:127], v[208:209], 0, s[52:53]
	s_add_i32 s10, s5, s41
	s_mov_b32 s11, m0
	s_mov_b32 m0, s10
	s_nop 0
	global_load_lds_dwordx4 v[126:127], off
	s_mov_b32 m0, s11
	s_mov_b64 s[10:11], 0x7078200
	v_lshl_add_u64 v[126:127], v[206:207], 0, s[10:11]
	s_lshl_b32 s10, s88, 1
	s_add_i32 s58, s10, s57
	s_mov_b32 s10, m0
	s_mov_b32 m0, s58
	s_nop 0
	global_load_lds_dwordx4 v[126:127], off
	s_mov_b32 m0, s10
	s_mov_b64 s[10:11], 0x7078280
	v_lshl_add_u64 v[126:127], v[206:207], 0, s[10:11]
	s_add_i32 s10, s58, 0x2000
	s_mov_b32 s11, m0
	s_mov_b32 m0, s10
	s_nop 0
	global_load_lds_dwordx4 v[126:127], off
	s_mov_b32 m0, s11
	v_max_f32_e32 v126, v98, v99
	v_max3_f32 v127, v100, v101, v83
	v_max3_f32 v126, v126, v82, v84
	v_max3_f32 v126, v126, v85, v102
	v_max3_f32 v127, v127, v104, v105
	v_max3_f32 v126, v126, v103, v86
	v_max3_f32 v127, v127, v88, v89
	v_max3_f32 v126, v126, v87, v106
	v_max3_f32 v127, v127, v108, v109
	v_max3_f32 v126, v126, v107, v90
	v_max3_f32 v127, v127, v92, v93
	v_max3_f32 v126, v126, v91, v110
	v_max3_f32 v127, v127, v112, v113
	v_max3_f32 v126, v126, v111, v94
	v_max3_f32 v127, v127, v96, v97
	v_max3_f32 v126, v126, v95, v127
	v_mov_b32_e32 v127, v126
	s_nop 1
	v_permlane32_swap_b32_e32 v126, v127
	v_max_f32_e32 v126, v126, v127
	v_cmp_lt_f32_e32 vcc, s84, v126
	s_cmp_lg_u64 vcc, 0
	v_add_f32_e32 v238, v238, v134
	s_cselect_b64 s[58:59], -1, 0
	s_cbranch_vccnz .LBB0_428

.LBB0_491:
	v_add_u32_e32 v190, s4, v243
	ds_read_b64_tr_b16 v[178:179], v190 offset:24576
	ds_read_b64_tr_b16 v[180:181], v190 offset:25088
	s_waitcnt lgkmcnt(9)
	v_mfma_f32_32x32x16_bf16 v[98:113], v[174:177], v[142:145], v[34:49]
	v_add_f32_e32 v82, v66, v67
	v_add_f32_e32 v82, v68, v82
	v_add_f32_e32 v82, v69, v82
	v_add_f32_e32 v82, v70, v82
	v_add_f32_e32 v82, v71, v82
	v_cvt_pk_bf16_f32 v138, v66, v67
	v_cvt_pk_bf16_f32 v139, v68, v69
	ds_read_b64_tr_b16 v[174:175], v190 offset:28672
	ds_read_b64_tr_b16 v[176:177], v190 offset:29184
	v_add_f32_e32 v66, v72, v82
	s_waitcnt lgkmcnt(10)
	v_mfma_f32_32x32x16_bf16 v[82:97], v[170:173], v[142:145], v[34:49]
	v_add_f32_e32 v66, v73, v66
	v_add_f32_e32 v66, v74, v66
	v_add_f32_e32 v118, v75, v66
	v_cvt_pk_bf16_f32 v140, v70, v71
	v_cvt_pk_bf16_f32 v141, v72, v73
	ds_read_b64_tr_b16 v[66:67], v190 offset:25600
	ds_read_b64_tr_b16 v[68:69], v190 offset:26112
	s_waitcnt lgkmcnt(11)
	v_mfma_f32_32x32x16_bf16 v[98:113], v[166:169], v[130:133], v[98:113]
	v_add_f32_e32 v70, v76, v118
	v_add_f32_e32 v70, v77, v70
	v_add_f32_e32 v70, v78, v70
	v_add_f32_e32 v118, v79, v70
	v_cvt_pk_bf16_f32 v134, v74, v75
	v_cvt_pk_bf16_f32 v135, v76, v77
	ds_read_b64_tr_b16 v[70:71], v190 offset:29696
	ds_read_b64_tr_b16 v[72:73], v190 offset:30208
	s_waitcnt lgkmcnt(12)
	v_mfma_f32_32x32x16_bf16 v[82:97], v[162:165], v[130:133], v[82:97]
	v_add_f32_e32 v74, v80, v118
	v_add_f32_e32 v74, v81, v74
	v_add_f32_e32 v74, v50, v74
	v_add_f32_e32 v118, v51, v74
	v_cvt_pk_bf16_f32 v136, v78, v79
	v_cvt_pk_bf16_f32 v137, v80, v81
	ds_read_b64_tr_b16 v[74:75], v190 offset:26624
	ds_read_b64_tr_b16 v[76:77], v190 offset:27136
	s_waitcnt lgkmcnt(13)
	v_mfma_f32_32x32x16_bf16 v[98:113], v[158:161], v[122:125], v[98:113]
	v_add_f32_e32 v78, v52, v118
	v_add_f32_e32 v78, v53, v78
	v_add_f32_e32 v78, v54, v78
	v_add_f32_e32 v78, v55, v78
	v_cvt_pk_bf16_f32 v126, v50, v51
	v_cvt_pk_bf16_f32 v127, v52, v53
	ds_read_b64_tr_b16 v[50:51], v190 offset:30720
	ds_read_b64_tr_b16 v[52:53], v190 offset:31232
	s_waitcnt lgkmcnt(14)
	v_mfma_f32_32x32x16_bf16 v[82:97], v[154:157], v[122:125], v[82:97]
	v_add_f32_e32 v78, v56, v78
	v_add_f32_e32 v78, v57, v78
	v_add_f32_e32 v78, v58, v78
	v_add_f32_e32 v78, v59, v78
	v_cvt_pk_bf16_f32 v128, v54, v55
	v_cvt_pk_bf16_f32 v129, v56, v57
	ds_read_b64_tr_b16 v[54:55], v190 offset:27648
	ds_read_b64_tr_b16 v[56:57], v190 offset:28160
	s_waitcnt lgkmcnt(14)
	v_mfma_f32_32x32x16_bf16 v[98:113], v[150:153], v[114:117], v[98:113]
	v_add_f32_e32 v78, v60, v78
	v_add_f32_e32 v78, v61, v78
	v_add_f32_e32 v78, v62, v78
	v_add_f32_e32 v78, v63, v78
	v_cvt_pk_bf16_f32 v118, v58, v59
	v_cvt_pk_bf16_f32 v119, v60, v61
	ds_read_b64_tr_b16 v[58:59], v190 offset:31744
	ds_read_b64_tr_b16 v[60:61], v190 offset:32256
	v_mfma_f32_32x32x16_bf16 v[82:97], v[146:149], v[114:117], v[82:97]
	v_add_f32_e32 v78, v64, v78
	v_add_f32_e32 v78, v65, v78
	v_cvt_pk_bf16_f32 v120, v62, v63
	v_cvt_pk_bf16_f32 v121, v64, v65
	v_lshl_add_u64 v[62:63], v[188:189], 0, s[54:55]
	s_add_i32 s4, s40, s37
	s_mov_b32 s5, m0
	s_mov_b32 m0, s4
	s_nop 0
	global_load_lds_dwordx4 v[62:63], off
	s_mov_b32 m0, s5
	v_lshl_add_u64 v[62:63], v[186:187], 0, s[54:55]
	s_add_i32 s4, s20, s38
	s_mov_b32 s5, m0
	s_mov_b32 m0, s4
	s_nop 0
	global_load_lds_dwordx4 v[62:63], off
	s_mov_b32 m0, s5
	v_max_f32_e32 v62, v98, v99
	v_max3_f32 v63, v100, v101, v83
	v_max3_f32 v62, v62, v82, v84
	v_max3_f32 v62, v62, v85, v102
	v_max3_f32 v63, v63, v104, v105
	v_max3_f32 v62, v62, v103, v86
	v_max3_f32 v63, v63, v88, v89
	v_max3_f32 v62, v62, v87, v106
	v_max3_f32 v63, v63, v108, v109
	v_max3_f32 v62, v62, v107, v90
	v_max3_f32 v63, v63, v92, v93
	v_max3_f32 v62, v62, v91, v110
	v_max3_f32 v63, v63, v112, v113
	v_max3_f32 v62, v62, v111, v94
	v_max3_f32 v63, v63, v96, v97
	v_max3_f32 v62, v62, v95, v63
	v_mov_b32_e32 v63, v62
	s_nop 1
	v_permlane32_swap_b32_e32 v62, v63
	v_max_f32_e32 v62, v62, v63
	v_cmp_lt_f32_e32 vcc, s84, v62
	s_cmp_lg_u64 vcc, 0
	v_add_f32_e32 v190, v195, v78
	s_cselect_b64 s[4:5], -1, 0
	s_cbranch_vccnz .LBB0_499

.LBB0_494:
	s_add_i32 s4, s20, 0x2000
	s_cmpk_lg_i32 s20, 0x4000
	s_cselect_b32 s39, s4, 0
	v_add_u32_e32 v191, s40, v243
	ds_read_b64_tr_b16 v[150:151], v191 offset:24576
	ds_read_b64_tr_b16 v[152:153], v191 offset:25088
	s_waitcnt lgkmcnt(9)
	v_mfma_f32_32x32x16_bf16 v[66:81], v[62:65], v[142:145], v[34:49]
	v_add_f32_e32 v50, v98, v99
	v_add_f32_e32 v50, v100, v50
	v_add_f32_e32 v50, v101, v50
	v_add_f32_e32 v50, v102, v50
	v_add_f32_e32 v50, v103, v50
	v_cvt_pk_bf16_f32 v138, v98, v99
	v_cvt_pk_bf16_f32 v139, v100, v101
	ds_read_b64_tr_b16 v[146:147], v191 offset:28672
	ds_read_b64_tr_b16 v[148:149], v191 offset:29184
	v_add_f32_e32 v50, v104, v50
	v_add_f32_e32 v50, v105, v50
	v_add_f32_e32 v50, v106, v50
	v_add_f32_e32 v118, v107, v50
	s_waitcnt lgkmcnt(10)
	v_mfma_f32_32x32x16_bf16 v[50:65], v[174:177], v[142:145], v[34:49]
	v_cvt_pk_bf16_f32 v140, v102, v103
	v_cvt_pk_bf16_f32 v141, v104, v105
	ds_read_b64_tr_b16 v[98:99], v191 offset:25600
	ds_read_b64_tr_b16 v[100:101], v191 offset:26112
	s_waitcnt lgkmcnt(11)
	v_mfma_f32_32x32x16_bf16 v[66:81], v[178:181], v[130:133], v[66:81]
	v_add_f32_e32 v102, v108, v118
	v_add_f32_e32 v102, v109, v102
	v_add_f32_e32 v102, v110, v102
	v_add_f32_e32 v118, v111, v102
	v_cvt_pk_bf16_f32 v134, v106, v107
	v_cvt_pk_bf16_f32 v135, v108, v109
	ds_read_b64_tr_b16 v[102:103], v191 offset:29696
	ds_read_b64_tr_b16 v[104:105], v191 offset:30208
	s_waitcnt lgkmcnt(12)
	v_mfma_f32_32x32x16_bf16 v[50:65], v[170:173], v[130:133], v[50:65]
	v_add_f32_e32 v106, v112, v118
	v_add_f32_e32 v106, v113, v106
	v_add_f32_e32 v106, v82, v106
	v_add_f32_e32 v118, v83, v106
	v_cvt_pk_bf16_f32 v136, v110, v111
	v_cvt_pk_bf16_f32 v137, v112, v113
	ds_read_b64_tr_b16 v[106:107], v191 offset:26624
	ds_read_b64_tr_b16 v[108:109], v191 offset:27136
	s_waitcnt lgkmcnt(13)
	v_mfma_f32_32x32x16_bf16 v[66:81], v[166:169], v[122:125], v[66:81]
	v_add_f32_e32 v110, v84, v118
	v_add_f32_e32 v110, v85, v110
	v_add_f32_e32 v110, v86, v110
	v_add_f32_e32 v110, v87, v110
	v_cvt_pk_bf16_f32 v126, v82, v83
	v_cvt_pk_bf16_f32 v127, v84, v85
	ds_read_b64_tr_b16 v[82:83], v191 offset:30720
	ds_read_b64_tr_b16 v[84:85], v191 offset:31232
	s_waitcnt lgkmcnt(14)
	v_mfma_f32_32x32x16_bf16 v[50:65], v[162:165], v[122:125], v[50:65]
	v_add_f32_e32 v110, v88, v110
	v_add_f32_e32 v110, v89, v110
	v_add_f32_e32 v110, v90, v110
	v_add_f32_e32 v110, v91, v110
	v_cvt_pk_bf16_f32 v128, v86, v87
	v_cvt_pk_bf16_f32 v129, v88, v89
	ds_read_b64_tr_b16 v[86:87], v191 offset:27648
	ds_read_b64_tr_b16 v[88:89], v191 offset:28160
	s_waitcnt lgkmcnt(14)
	v_mfma_f32_32x32x16_bf16 v[66:81], v[158:161], v[114:117], v[66:81]
	v_add_f32_e32 v110, v92, v110
	v_add_f32_e32 v110, v93, v110
	v_add_f32_e32 v110, v94, v110
	v_add_f32_e32 v110, v95, v110
	v_cvt_pk_bf16_f32 v118, v90, v91
	v_cvt_pk_bf16_f32 v119, v92, v93
	ds_read_b64_tr_b16 v[90:91], v191 offset:31744
	ds_read_b64_tr_b16 v[92:93], v191 offset:32256
	v_mfma_f32_32x32x16_bf16 v[50:65], v[154:157], v[114:117], v[50:65]
	v_add_f32_e32 v110, v96, v110
	v_add_f32_e32 v110, v97, v110
	v_cvt_pk_bf16_f32 v120, v94, v95
	v_cvt_pk_bf16_f32 v121, v96, v97
	v_max_f32_e32 v94, v66, v67
	s_nop 3
	v_max3_f32 v95, v68, v69, v51
	v_max3_f32 v94, v94, v50, v52
	v_max3_f32 v94, v94, v53, v70
	v_max3_f32 v95, v95, v72, v73
	v_max3_f32 v94, v94, v71, v54
	v_max3_f32 v95, v95, v56, v57
	v_max3_f32 v94, v94, v55, v74
	v_max3_f32 v95, v95, v76, v77
	v_max3_f32 v94, v94, v75, v58
	v_max3_f32 v95, v95, v60, v61
	v_max3_f32 v94, v94, v59, v78
	v_max3_f32 v95, v95, v80, v81
	v_max3_f32 v94, v94, v79, v62
	v_max3_f32 v95, v95, v64, v65
	v_max3_f32 v94, v94, v63, v95
	v_mov_b32_e32 v95, v94
	s_nop 1
	v_permlane32_swap_b32_e32 v94, v95
	s_add_i32 s4, s20, s37
	s_mov_b32 s5, m0
	s_mov_b32 m0, s4
	s_nop 0
	global_load_lds_dwordx4 v[188:189], off
	s_mov_b32 m0, s5
	v_max_f32_e32 v94, v94, v95
	s_add_i32 s4, s39, s38
	s_mov_b32 s5, m0
	s_mov_b32 m0, s4
	s_nop 0
	global_load_lds_dwordx4 v[186:187], off
	s_mov_b32 m0, s5
	v_cmp_lt_f32_e32 vcc, s84, v94
	s_cmp_lg_u64 vcc, 0
	v_add_f32_e32 v195, v190, v110
	s_cselect_b64 s[4:5], -1, 0
	s_cbranch_vccnz .LBB0_502
